# loop-edge edit: hipcc's redundant cndmask+cmp_ne ballot in the NSA selected-branch loop replaced by s_cmp on the mask it already has (2 sites)
# speedup vs baseline: 1.0096x; 1.0032x over previous
; template <int MODE, int TM> ...
;     ...
;   __builtin_amdgcn_s_setprio(1);
; #pragma unroll
;   for (int t = 0; t < 2; ++t) {
;     if (!(TM & (1 << t))) continue;
;     const h16* Ks = t ? Ks1 : Ks0;
; #pragma unroll
;     for (int kt = 0; kt < 4; ++kt) {
;       S[t][kt] = f32x4{0.f, 0.f, 0.f, 0.f};
; #pragma unroll
;       for (int ks = 0; ks < 2; ++ks) {
;         h16x8 Kf = *(const h16x8*)(Ks + (kt * 16 + col) * KP + ks * 32 + q4 * 8);
;         S[t][kt] = __builtin_amdgcn_mfma_f32_16x16x32_f16(Kf, Q[ks], S[t][kt], 0, 0, 0);
;       }
;     }
;   }
;   __builtin_amdgcn_s_setprio(0);
;     ...
;         const int jb = 2 * i;
;         bool sb[2];
;         sb[0] = ((jb < 64 ? (slo >> jb) : (shi >> (jb - 64))) & 1ull) != 0;
;         sb[1] = (jb + 1 <= cur) && (((jb + 1 < 64 ? (slo >> (jb + 1)) : (shi >> (jb + 1 - 64))) & 1ull) != 0);
;         const bool far[2] = {t0 - (jb * 64 + 63) >= 799, t0 - (jb * 64 + 127) >= 799};
;         const bool n0 = __any(sb[0]) != 0, n1 = __any(sb[1]) != 0;
;         if (n0 && n1) attn_tile2<M_SEL, 3>(Q, O, st, KSB(i, 0), VTB(i, 0), KSB(i, 1), VTB(i, 1), biasT, tq, hd, jb * 64, far, sb, hpd, hpe, lane);
;         else if (n0) attn_tile2<M_SEL, 1>(Q, O, st, KSB(i, 0), VTB(i, 0), KSB(i, 1), VTB(i, 1), biasT, tq, hd, jb * 64, far, sb, hpd, hpe, lane);
;         else if (n1) attn_tile2<M_SEL, 2>(Q, O, st, KSB(i, 0), VTB(i, 0), KSB(i, 1), VTB(i, 1), biasT, tq, hd, jb * 64, far, sb, hpd, hpe, lane);
.LBB0_1439:
	s_lshl_b32 s2, s30, 1
	s_cmp_lt_u32 s30, 32
	s_cselect_b64 s[42:43], -1, 0
	s_sub_i32 s3, s2, 64
	s_and_b64 s[0:1], s[42:43], exec
	v_cndmask_b32_e64 v3, v47, v45, s[42:43]
	s_cselect_b32 s0, s2, s3
	v_cndmask_b32_e64 v2, v46, v44, s[42:43]
	s_cmp_lt_u32 s2, s28
	v_lshrrev_b64 v[80:81], s0, v[2:3]
	s_cselect_b64 s[0:1], -1, 0
	s_or_b32 s46, s2, 1
	s_sub_i32 s47, s2, 63
	s_and_b64 s[2:3], s[42:43], exec
	s_cselect_b32 s2, s46, s47
	s_lshl_b64 s[2:3], 1, s2
	v_and_b32_e32 v83, s3, v3
	v_and_b32_e32 v82, s2, v2
	v_cmp_ne_u64_e32 vcc, 0, v[82:83]
	s_lshl_b32 s2, s30, 7
	s_and_b64 s[46:47], s[0:1], vcc
	s_sub_i32 s0, s20, s2
	s_cmpk_lt_i32 s0, 0x35e
	v_and_b32_e32 v0, 1, v80
	s_cselect_b64 s[50:51], -1, 0
	s_cmpk_lt_i32 s0, 0x39e
	v_cmp_ne_u32_e32 vcc, 0, v0
	s_cselect_b64 s[48:49], -1, 0
	s_cmp_eq_u64 vcc, 0
	v_cndmask_b32_e64 v80, 0, 1, s[46:47]
	s_cselect_b64 s[0:1], -1, 0
	s_cmp_lg_u64 vcc, 0
	s_nop 0
	s_cselect_b64 s[56:57], -1, 0
	s_cmp_lg_u64 s[46:47], 0
	s_cselect_b64 s[52:53], -1, 0
	s_and_b64 s[56:57], s[56:57], s[52:53]
	s_andn2_b64 vcc, exec, s[56:57]
	s_cbranch_vccz .LBB0_1480
	s_and_b64 vcc, exec, s[0:1]
	s_cbranch_vccz .LBB0_1481
	v_mov_b64_e32 v[82:83], v[30:31]
	v_mov_b64_e32 v[86:87], v[34:35]
	v_mov_b64_e32 v[90:91], v[38:39]
	v_mov_b64_e32 v[94:95], v[42:43]
	s_mov_b64 s[0:1], 0
	s_and_b64 vcc, exec, s[52:53]
	v_mov_b32_e32 v188, v243
	v_mov_b32_e32 v244, v173
	v_mov_b64_e32 v[80:81], v[28:29]
	v_mov_b64_e32 v[84:85], v[32:33]
	v_mov_b64_e32 v[88:89], v[36:37]
	v_mov_b64_e32 v[92:93], v[40:41]
	s_mov_b64 s[52:53], 0
	s_cbranch_vccz .LBB0_1482
	s_nop 0
	ds_read_b128 v[80:83], v155 offset:33280
	ds_read_b128 v[84:87], v155 offset:33344
	ds_read_b128 v[88:91], v155 offset:35840
	ds_read_b128 v[92:95], v155 offset:35904
	ds_read_b128 v[96:99], v155 offset:38400
	s_waitcnt lgkmcnt(4)
	v_mfma_f32_16x16x32_f16 v[80:83], v[80:83], v[4:7], 0
	s_waitcnt lgkmcnt(2)
	v_mfma_f32_16x16x32_f16 v[88:91], v[88:91], v[4:7], 0
	v_mfma_f32_16x16x32_f16 v[84:87], v[84:87], v[8:11], v[80:83]
	s_waitcnt lgkmcnt(1)
	v_mfma_f32_16x16x32_f16 v[80:83], v[92:95], v[8:11], v[88:91]
	s_nop 4
	ds_read_b128 v[88:91], v155 offset:38464
	s_waitcnt lgkmcnt(1)
	v_mfma_f32_16x16x32_f16 v[92:95], v[96:99], v[4:7], 0
	ds_read_b128 v[96:99], v155 offset:40960
	s_waitcnt lgkmcnt(1)
	v_mfma_f32_16x16x32_f16 v[92:95], v[88:91], v[8:11], v[92:95]
	ds_read_b128 v[88:91], v155 offset:41024
	s_waitcnt lgkmcnt(1)
	v_mfma_f32_16x16x32_f16 v[96:99], v[96:99], v[4:7], 0
	s_waitcnt lgkmcnt(0)
	v_mfma_f32_16x16x32_f16 v[88:91], v[88:91], v[8:11], v[96:99]
	s_nop 0
	s_andn2_b64 vcc, exec, s[48:49]
	s_mov_b64 s[52:53], -1
	s_cbranch_vccnz .LBB0_1476
	v_or_b32_e32 v112, s2, v154
	s_nop 0
	v_sub_u32_e32 v98, v175, v112
	v_cmp_lt_i32_e32 vcc, -1, v98
	s_and_b64 s[56:57], vcc, s[46:47]
	v_mov_b32_e32 v97, 0xf149f2ca
	v_mov_b32_e32 v96, 0xf149f2ca
	s_and_saveexec_b64 s[52:53], s[56:57]
	s_cbranch_execz .LBB0_1445
	v_min_u32_e32 v96, 0x31f, v98
	v_lshl_add_u32 v96, v96, 2, v157
	ds_read_b32 v96, v96

; template <int MODE, int TM> ...
;     ...
;   __builtin_amdgcn_s_setprio(1);
; #pragma unroll
;   for (int t = 0; t < 2; ++t) {
;     if (!(TM & (1 << t))) continue;
;     const h16* Ks = t ? Ks1 : Ks0;
; #pragma unroll
;     for (int kt = 0; kt < 4; ++kt) {
;       S[t][kt] = f32x4{0.f, 0.f, 0.f, 0.f};
; #pragma unroll
;       for (int ks = 0; ks < 2; ++ks) {
;         h16x8 Kf = *(const h16x8*)(Ks + (kt * 16 + col) * KP + ks * 32 + q4 * 8);
;         S[t][kt] = __builtin_amdgcn_mfma_f32_16x16x32_f16(Kf, Q[ks], S[t][kt], 0, 0, 0);
;       }
;     }
;   }
;   __builtin_amdgcn_s_setprio(0);
;     ...
;         const int jb = 2 * i;
;         bool sb[2];
;         sb[0] = ((jb < 64 ? (slo >> jb) : (shi >> (jb - 64))) & 1ull) != 0;
;         sb[1] = (jb + 1 <= cur) && (((jb + 1 < 64 ? (slo >> (jb + 1)) : (shi >> (jb + 1 - 64))) & 1ull) != 0);
;         const bool far[2] = {t0 - (jb * 64 + 63) >= 799, t0 - (jb * 64 + 127) >= 799};
;         const bool n0 = __any(sb[0]) != 0, n1 = __any(sb[1]) != 0;
;         if (n0 && n1) attn_tile2<M_SEL, 3>(Q, O, st, KSB(i, 0), VTB(i, 0), KSB(i, 1), VTB(i, 1), biasT, tq, hd, jb * 64, far, sb, hpd, hpe, lane);
;         else if (n0) attn_tile2<M_SEL, 1>(Q, O, st, KSB(i, 0), VTB(i, 0), KSB(i, 1), VTB(i, 1), biasT, tq, hd, jb * 64, far, sb, hpd, hpe, lane);
;         else if (n1) attn_tile2<M_SEL, 2>(Q, O, st, KSB(i, 0), VTB(i, 0), KSB(i, 1), VTB(i, 1), biasT, tq, hd, jb * 64, far, sb, hpd, hpe, lane);
.LBB0_1618:
	s_lshl_b32 s2, s31, 1
	s_sub_i32 s3, s2, 64
	s_and_b64 s[0:1], s[42:43], exec
	s_cselect_b32 s0, s2, s3
	s_cmp_lt_u32 s2, s28
	v_lshrrev_b64 v[28:29], s0, v[2:3]
	s_cselect_b64 s[0:1], -1, 0
	s_or_b32 s44, s2, 1
	s_sub_i32 s45, s2, 63
	s_and_b64 s[2:3], s[42:43], exec
	s_cselect_b32 s2, s44, s45
	s_lshl_b64 s[2:3], 1, s2
	v_and_b32_e32 v3, s3, v3
	v_and_b32_e32 v2, s2, v2
	v_cmp_ne_u64_e32 vcc, 0, v[2:3]
	s_lshl_b32 s2, s31, 7
	s_and_b64 s[42:43], s[0:1], vcc
	s_sub_i32 s0, s20, s2
	s_cmpk_lt_i32 s0, 0x35e
	v_and_b32_e32 v0, 1, v28
	s_cselect_b64 s[46:47], -1, 0
	s_cmpk_lt_i32 s0, 0x39e
	v_cmp_ne_u32_e32 vcc, 0, v0
	s_cselect_b64 s[44:45], -1, 0
	s_cmp_eq_u64 vcc, 0
	v_cndmask_b32_e64 v2, 0, 1, s[42:43]
	s_cselect_b64 s[0:1], -1, 0
	s_cmp_lg_u64 vcc, 0
	s_nop 0
	s_cselect_b64 s[50:51], -1, 0
	s_cmp_lg_u64 s[42:43], 0
	s_cselect_b64 s[48:49], -1, 0
	s_and_b64 s[50:51], s[50:51], s[48:49]
	s_and_b64 vcc, exec, s[50:51]
	s_cbranch_vccnz .LBB0_1660
	s_and_b64 vcc, exec, s[0:1]
	s_cbranch_vccz .LBB0_1661
	v_mov_b64_e32 v[28:29], v[80:81]
	v_mov_b64_e32 v[32:33], v[84:85]
	v_mov_b64_e32 v[36:37], v[88:89]
	v_mov_b64_e32 v[40:41], v[92:93]
	s_mov_b64 s[0:1], 0
	s_and_b64 vcc, exec, s[48:49]
	v_mov_b32_e32 v243, v188
	v_mov_b32_e32 v173, v244
	v_mov_b64_e32 v[30:31], v[82:83]
	v_mov_b64_e32 v[34:35], v[86:87]
	v_mov_b64_e32 v[38:39], v[90:91]
	v_mov_b64_e32 v[42:43], v[94:95]
	s_mov_b64 s[48:49], 0
	s_cbranch_vccz .LBB0_1662
	s_nop 0
	ds_read_b128 v[28:31], v202
	ds_read_b128 v[32:35], v202 offset:64
	ds_read_b128 v[36:39], v202 offset:2560
	ds_read_b128 v[40:43], v202 offset:2624
	ds_read_b128 v[96:99], v202 offset:5120
	s_waitcnt lgkmcnt(4)
	v_mfma_f32_16x16x32_f16 v[28:31], v[28:31], v[4:7], 0
	s_waitcnt lgkmcnt(2)
	v_mfma_f32_16x16x32_f16 v[36:39], v[36:39], v[4:7], 0
	v_mfma_f32_16x16x32_f16 v[32:35], v[32:35], v[8:11], v[28:31]
	s_waitcnt lgkmcnt(1)
	v_mfma_f32_16x16x32_f16 v[28:31], v[40:43], v[8:11], v[36:39]
	s_nop 4
	ds_read_b128 v[36:39], v202 offset:5184
	s_waitcnt lgkmcnt(1)
	v_mfma_f32_16x16x32_f16 v[40:43], v[96:99], v[4:7], 0
	ds_read_b128 v[96:99], v202 offset:7680
	s_waitcnt lgkmcnt(1)
	v_mfma_f32_16x16x32_f16 v[40:43], v[36:39], v[8:11], v[40:43]
	ds_read_b128 v[36:39], v202 offset:7744
	s_waitcnt lgkmcnt(1)
	v_mfma_f32_16x16x32_f16 v[96:99], v[96:99], v[4:7], 0
	s_waitcnt lgkmcnt(0)
	v_mfma_f32_16x16x32_f16 v[36:39], v[36:39], v[8:11], v[96:99]
	s_nop 0
	s_andn2_b64 vcc, exec, s[44:45]
	s_mov_b64 s[48:49], -1
	s_cbranch_vccnz .LBB0_1655
	v_or_b32_e32 v2, s2, v154
	v_sub_u32_e32 v3, v175, v2
	v_cmp_lt_i32_e32 vcc, -1, v3
	s_and_b64 s[50:51], vcc, s[42:43]
	v_mov_b32_e32 v97, 0xf149f2ca
	v_mov_b32_e32 v96, 0xf149f2ca
	s_and_saveexec_b64 s[48:49], s[50:51]
	s_cbranch_execz .LBB0_1624
	v_min_u32_e32 v3, 0x31f, v3
	v_lshl_add_u32 v3, v3, 2, v157
	ds_read_b32 v96, v3
